# stack: batched sample-unit epilogues (ph 4,9,12), retb output loads batched, conv LN gain/bias loaded once, la_items waits count out the previous item's stores
# speedup vs baseline: 1.0016x; 1.0016x over previous
.LBB0_715:
	s_cmp_gt_i32 s34, 48
	s_cselect_b32 s0, 24, 0
	s_cmp_lt_i32 s2, s0
	s_cbranch_scc1 .LBB0_782
	s_sub_i32 s1, s34, s0
	s_abs_i32 s3, s1
	s_waitcnt vmcnt(0)
	v_cvt_f32_u32_e32 v0, s3
	s_sub_i32 s5, 0, s3
	s_sub_i32 s4, s2, s0
	s_ashr_i32 s0, s1, 31
	v_rcp_iflag_f32_e32 v0, v0
	s_nop 0
	v_mul_f32_e32 v0, 0x4f7ffffe, v0
	v_cvt_u32_f32_e32 v0, v0
	s_nop 0
	v_readfirstlane_b32 s6, v0
	s_mul_i32 s5, s5, s6
	s_mul_hi_u32 s5, s6, s5
	s_add_i32 s6, s6, s5
	s_lshr_b32 s5, s6, 22
	s_mul_i32 s6, s5, s3
	s_sub_i32 s6, 0x400, s6
	s_add_i32 s7, s5, 1
	s_sub_i32 s8, s6, s3
	s_cmp_ge_u32 s6, s3
	s_cselect_b32 s5, s7, s5
	s_cselect_b32 s6, s8, s6
	s_add_i32 s7, s5, 1
	s_cmp_ge_u32 s6, s3
	s_cselect_b32 s3, s7, s5
	s_xor_b32 s3, s3, s0
	s_sub_i32 s5, s3, s0
	s_mul_i32 s0, s5, s1
	s_sub_i32 s6, 0x400, s0
	s_cmp_lt_i32 s4, s6
	s_mul_i32 s3, s5, s4
	s_cselect_b64 s[0:1], -1, 0
	s_min_i32 s4, s4, s6
	s_add_i32 s3, s4, s3
	s_cmp_lg_u64 s[0:1], 0
	s_addc_u32 s10, s3, s5
	s_add_i32 s1, s3, 1
	s_add_i32 s4, s10, 1
	s_ashr_i32 s0, s1, 1
	s_ashr_i32 s11, s4, 1
	s_cmp_ge_i32 s0, s11
	s_cbranch_scc1 .LBB0_726
	v_readfirstlane_b32 s4, v175
	s_lshr_b32 s8, s4, 6
	s_ashr_i32 s4, s1, 7
	s_ashr_i32 s5, s4, 31
	s_lshl_b32 s6, s0, 17
	s_lshl_b64 s[4:5], s[4:5], 21
	s_and_b32 s6, s6, 0x1e0000
	s_lshl_b32 s1, s0, 16
	s_or_b32 s4, s4, s6
	s_add_u32 s6, s36, s4
	s_addc_u32 s7, s37, s5
	s_lshl_b32 s12, s0, 4
	s_lshl_b32 s9, s0, 3
	s_and_b32 s12, s12, 0x300
	s_add_u32 s6, s6, s12
	s_addc_u32 s7, s7, 0
	s_add_u32 s4, s38, s4
	v_lshlrev_b32_e32 v0, 7, v175
	s_addc_u32 s5, s39, s5
	v_and_b32_e32 v36, 0x1fe00, v0
	v_lshlrev_b32_e32 v2, 5, v175
	s_add_u32 s4, s4, s12
	v_mov_b32_e32 v33, 0
	v_lshlrev_b32_e32 v32, 1, v36
	v_and_b32_e32 v42, 0x60, v2
	s_addc_u32 s5, s5, 0
	v_lshl_add_u64 v[0:1], s[6:7], 0, v[32:33]
	v_lshlrev_b32_e32 v34, 1, v42
	v_mov_b32_e32 v35, v33
	v_lshl_add_u64 v[16:17], s[4:5], 0, v[32:33]
	v_lshl_add_u64 v[12:13], v[0:1], 0, v[34:35]
	v_lshl_add_u64 v[28:29], v[16:17], 0, v[34:35]
	global_load_dwordx4 v[0:3], v[12:13], off offset:48
	global_load_dwordx4 v[4:7], v[12:13], off offset:32
	global_load_dwordx4 v[8:11], v[12:13], off offset:16
	s_nop 0
	global_load_dwordx4 v[12:15], v[12:13], off
	s_nop 0
	global_load_dwordx4 v[16:19], v[28:29], off offset:48
	global_load_dwordx4 v[20:23], v[28:29], off offset:32
	global_load_dwordx4 v[24:27], v[28:29], off offset:16
	s_nop 0
	global_load_dwordx4 v[28:31], v[28:29], off
	v_and_b32_e32 v32, 15, v175
	v_lshrrev_b32_e32 v35, 2, v175
	v_add_u32_e32 v37, 0, v34
	v_lshl_add_u32 v34, v32, 1, 0
	v_sub_u32_e32 v38, 0x7f, v35
	s_movk_i32 s4, 0x108
	v_mul_u32_u24_e32 v43, 0x108, v35
	v_and_b32_e32 v35, 12, v35
	v_lshlrev_b32_e32 v32, 7, v32
	s_add_i32 s13, s1, 0x10000
	s_ashr_i32 s1, s0, 31
	v_mad_u32_u24 v39, v35, s4, v34
	s_lshl_b64 s[4:5], s[0:1], 16
	v_lshl_or_b32 v40, s8, 11, v32
	v_cvt_f32_i32_e32 v38, v38
	v_lshl_add_u32 v44, s8, 5, v34
	v_mul_u32_u24_e32 v45, 0x108, v35
	v_and_or_b32 v34, v175, 48, s4
	v_mov_b32_e32 v35, s5
	v_ashrrev_i32_e32 v41, 31, v40
	v_lshl_add_u64 v[34:35], v[40:41], 2, v[34:35]
	v_lshl_add_u64 v[34:35], s[94:95], 0, v[34:35]
	s_mov_b64 s[4:5], 0x100100
	s_add_i32 s12, s9, 8
	v_lshl_add_u64 v[34:35], v[34:35], 0, s[4:5]
	v_add_u32_e32 v40, v37, v43
	v_lshlrev_b32_e32 v32, 1, v36
	v_lshlrev_b32_e32 v36, 1, v42
	v_add_u32_e32 v41, v44, v45
	s_mov_b32 s1, 0x5040100
	s_mov_b64 s[4:5], 0x10000
	v_mov_b32_e32 v42, 0xbbb906ce
	v_mov_b32_e32 v43, 0xbc3963dd
	s_waitcnt vmcnt(0)
	s_branch .LBB0_719

.LBB0_724:
	v_mul_f32_e32 v37, v37, v38
	v_exp_f32_e32 v37, v37
	s_waitcnt vmcnt(12)
	v_lshlrev_b32_e32 v44, 16, v12
	v_and_b32_e32 v45, 0xffff0000, v12
	v_and_b32_e32 v46, 0xffff0000, v13
	v_mul_f32_e32 v44, v37, v44
	v_mul_f32_e32 v45, v37, v45
	v_cvt_pk_bf16_f32 v44, v44, v45
	v_lshlrev_b32_e32 v45, 16, v13
	v_mul_f32_e32 v45, v37, v45
	v_mul_f32_e32 v46, v37, v46
	v_cvt_pk_bf16_f32 v45, v45, v46
	v_lshlrev_b32_e32 v46, 16, v14
	v_and_b32_e32 v47, 0xffff0000, v14
	v_mul_f32_e32 v46, v37, v46
	v_mul_f32_e32 v47, v37, v47
	v_cvt_pk_bf16_f32 v46, v46, v47
	v_lshlrev_b32_e32 v47, 16, v15
	v_mul_f32_e32 v47, v37, v47
	v_and_b32_e32 v48, 0xffff0000, v15
	v_mul_f32_e32 v48, v37, v48
	v_cvt_pk_bf16_f32 v47, v47, v48
	ds_write2_b64 v40, v[44:45], v[46:47] offset1:1
	v_lshlrev_b32_e32 v44, 16, v8
	v_and_b32_e32 v45, 0xffff0000, v8
	v_mul_f32_e32 v44, v37, v44
	v_mul_f32_e32 v45, v37, v45
	v_cvt_pk_bf16_f32 v44, v44, v45
	v_lshlrev_b32_e32 v45, 16, v9
	v_and_b32_e32 v46, 0xffff0000, v9
	v_mul_f32_e32 v45, v37, v45
	v_mul_f32_e32 v46, v37, v46
	v_cvt_pk_bf16_f32 v45, v45, v46
	v_lshlrev_b32_e32 v46, 16, v10
	v_and_b32_e32 v47, 0xffff0000, v10
	v_mul_f32_e32 v46, v37, v46
	v_mul_f32_e32 v47, v37, v47
	v_cvt_pk_bf16_f32 v46, v46, v47
	v_lshlrev_b32_e32 v47, 16, v11
	v_mul_f32_e32 v47, v37, v47
	v_and_b32_e32 v48, 0xffff0000, v11
	v_mul_f32_e32 v48, v37, v48
	v_cvt_pk_bf16_f32 v47, v47, v48
	ds_write2_b64 v40, v[44:45], v[46:47] offset0:2 offset1:3
	v_lshlrev_b32_e32 v44, 16, v4
	v_and_b32_e32 v45, 0xffff0000, v4
	v_mul_f32_e32 v44, v37, v44
	v_mul_f32_e32 v45, v37, v45
	v_cvt_pk_bf16_f32 v44, v44, v45
	v_lshlrev_b32_e32 v45, 16, v5
	v_and_b32_e32 v46, 0xffff0000, v5
	v_mul_f32_e32 v45, v37, v45
	v_mul_f32_e32 v46, v37, v46
	v_cvt_pk_bf16_f32 v45, v45, v46
	v_lshlrev_b32_e32 v46, 16, v6
	v_and_b32_e32 v47, 0xffff0000, v6
	v_mul_f32_e32 v46, v37, v46
	v_mul_f32_e32 v47, v37, v47
	v_cvt_pk_bf16_f32 v46, v46, v47
	v_lshlrev_b32_e32 v47, 16, v7
	v_mul_f32_e32 v47, v37, v47
	v_and_b32_e32 v48, 0xffff0000, v7
	v_mul_f32_e32 v48, v37, v48
	v_cvt_pk_bf16_f32 v47, v47, v48
	ds_write2_b64 v40, v[44:45], v[46:47] offset0:4 offset1:5
	v_lshlrev_b32_e32 v44, 16, v0
	v_and_b32_e32 v45, 0xffff0000, v0
	v_mul_f32_e32 v44, v37, v44
	v_mul_f32_e32 v45, v37, v45
	v_cvt_pk_bf16_f32 v44, v44, v45
	v_lshlrev_b32_e32 v45, 16, v1
	v_and_b32_e32 v46, 0xffff0000, v1
	v_mul_f32_e32 v45, v37, v45
	v_mul_f32_e32 v46, v37, v46
	v_cvt_pk_bf16_f32 v45, v45, v46
	v_lshlrev_b32_e32 v46, 16, v2
	v_and_b32_e32 v47, 0xffff0000, v2
	v_mul_f32_e32 v46, v37, v46
	v_mul_f32_e32 v47, v37, v47
	v_cvt_pk_bf16_f32 v46, v46, v47
	v_lshlrev_b32_e32 v47, 16, v3
	v_and_b32_e32 v48, 0xffff0000, v3
	v_mul_f32_e32 v47, v37, v47
	v_mul_f32_e32 v37, v37, v48
	v_cvt_pk_bf16_f32 v47, v47, v37
	v_add_u32_e32 v37, 0x8400, v40
	s_add_i32 s0, s0, 1
	s_waitcnt vmcnt(8)
	ds_write2_b64 v37, v[28:29], v[30:31] offset1:1
	v_add_u32_e32 v37, 0x8410, v40
	s_cmp_ge_i32 s0, s11
	ds_write2_b64 v37, v[24:25], v[26:27] offset1:1
	v_add_u32_e32 v37, 0x8420, v40
	s_cselect_b64 s[8:9], -1, 0
	ds_write2_b64 v37, v[20:21], v[22:23] offset1:1
	v_add_u32_e32 v37, 0x8430, v40
	s_and_b64 vcc, exec, s[8:9]
	ds_write2_b64 v40, v[44:45], v[46:47] offset0:6 offset1:7
	ds_write2_b64 v37, v[16:17], v[18:19] offset1:1
	s_cbranch_vccnz .LBB0_718
	s_ashr_i32 s6, s0, 6
	s_ashr_i32 s7, s6, 31
	s_and_b32 s14, s13, 0xf0000
	s_lshl_b64 s[6:7], s[6:7], 21
	s_lshl_b32 s14, s14, 1
	s_or_b32 s6, s6, s14
	s_add_u32 s14, s36, s6
	s_addc_u32 s15, s37, s7
	s_and_b32 s16, s12, 0x180
	s_lshl_b32 s16, s16, 1
	s_add_u32 s14, s14, s16
	s_addc_u32 s15, s15, 0
	s_add_u32 s6, s38, s6
	s_addc_u32 s7, s39, s7
	s_add_u32 s6, s6, s16
	s_addc_u32 s7, s7, 0
	v_lshl_add_u64 v[0:1], s[14:15], 0, v[32:33]
	v_mov_b32_e32 v37, v33
	v_lshl_add_u64 v[16:17], s[6:7], 0, v[32:33]
	v_lshl_add_u64 v[12:13], v[0:1], 0, v[36:37]
	v_lshl_add_u64 v[28:29], v[16:17], 0, v[36:37]
	global_load_dwordx4 v[0:3], v[12:13], off offset:48
	global_load_dwordx4 v[4:7], v[12:13], off offset:32
	global_load_dwordx4 v[8:11], v[12:13], off offset:16
	s_nop 0
	global_load_dwordx4 v[12:15], v[12:13], off
	s_nop 0
	global_load_dwordx4 v[16:19], v[28:29], off offset:48
	global_load_dwordx4 v[20:23], v[28:29], off offset:32
	global_load_dwordx4 v[24:27], v[28:29], off offset:16
	s_nop 0
	global_load_dwordx4 v[28:31], v[28:29], off
	s_branch .LBB0_718

.LBB0_744:
	v_lshlrev_b32_e32 v33, 1, v33
	v_add_u32_e32 v36, 0, v33
	v_lshlrev_b32_e32 v35, 4, v144
	v_add_u32_e32 v40, v36, v33
	v_mbcnt_lo_u32_b32 v33, -1, 0
	v_add_u32_e32 v119, 0, v35
	v_mbcnt_hi_u32_b32 v33, -1, v33
	v_add_u32_e32 v120, v119, v35
	v_and_b32_e32 v35, 64, v33
	v_add_u32_e32 v35, 64, v35
	v_xor_b32_e32 v41, 1, v33
	v_cmp_lt_i32_e32 vcc, v41, v35
	v_lshrrev_b32_e32 v37, 4, v175
	v_and_b32_e32 v38, 48, v37
	v_cndmask_b32_e32 v41, v33, v41, vcc
	v_lshlrev_b32_e32 v121, 2, v41
	v_xor_b32_e32 v41, 2, v33
	v_cmp_lt_i32_e32 vcc, v41, v35
	s_mov_b32 s0, 0xf800
	v_readlane_b32 s80, v254, 27
	v_cndmask_b32_e32 v41, v33, v41, vcc
	v_lshlrev_b32_e32 v122, 2, v41
	v_xor_b32_e32 v41, 4, v33
	v_cmp_lt_i32_e32 vcc, v41, v35
	v_lshlrev_b32_e32 v34, 2, v34
	v_readlane_b32 s81, v254, 28
	v_cndmask_b32_e32 v41, v33, v41, vcc
	v_lshlrev_b32_e32 v123, 2, v41
	v_xor_b32_e32 v41, 8, v33
	v_cmp_lt_i32_e32 vcc, v41, v35
	v_readlane_b32 s8, v254, 0
	s_lshl_b32 s1, s14, 10
	v_cndmask_b32_e32 v41, v33, v41, vcc
	v_lshlrev_b32_e32 v124, 2, v41
	v_xor_b32_e32 v41, 16, v33
	v_cmp_lt_i32_e32 vcc, v41, v35
	v_readlane_b32 s83, v254, 30
	v_readlane_b32 s94, v254, 41
	v_cndmask_b32_e32 v41, v33, v41, vcc
	v_lshlrev_b32_e32 v125, 2, v41
	v_xor_b32_e32 v41, 32, v33
	v_cmp_lt_i32_e32 vcc, v41, v35
	v_readlane_b32 s95, v254, 42
	v_readlane_b32 s10, v254, 2
	v_cndmask_b32_e32 v33, v33, v41, vcc
	v_lshlrev_b32_e32 v126, 2, v33
	v_lshlrev_b32_e32 v33, 11, v38
	v_add3_u32 v127, v40, v33, s0
	v_mov_b32_e32 v33, 0x7800
	v_lshl_or_b32 v37, v37, 11, v33
	v_mov_b32_e32 v33, 0
	v_mov_b32_e32 v35, v33
	v_lshl_add_u64 v[108:109], s[66:67], 0, v[34:35]
	v_lshl_add_u64 v[110:111], s[80:81], 0, v[34:35]
	global_load_dwordx4 v[228:231], v[108:109], off offset:16
	global_load_dwordx4 v[232:235], v[108:109], off
	global_load_dwordx4 v[236:239], v[110:111], off offset:16
	global_load_dwordx4 v[240:243], v[110:111], off
	v_lshlrev_b32_e32 v34, 2, v175
	v_readlane_b32 s11, v254, 3
	v_lshlrev_b32_e32 v39, 10, v38
	v_lshl_add_u64 v[106:107], s[30:31], 0, v[32:33]
	v_readlane_b32 s82, v254, 29
	s_mov_b32 s83, s1
	v_lshl_add_u64 v[34:35], s[10:11], 0, v[34:35]
	s_mov_b64 s[0:1], 0x4400000
	v_lshl_add_u64 v[114:115], s[24:25], 0, v[32:33]
	v_cndmask_b32_e64 v32, 0, 1, s[52:53]
	v_readlane_b32 s94, v254, 59
	s_lshl_b32 s29, s6, 11
	s_lshl_b32 s28, s6, 10
	s_lshl_b32 s42, s15, 10
	s_lshl_b32 s43, s16, 10
	s_lshl_b32 s44, s76, 10
	s_lshl_b32 s45, s17, 10
	s_lshl_b32 s46, s77, 10
	s_lshl_b32 s47, s5, 10
	v_lshl_add_u32 v128, v175, 1, 0
	s_lshl_b32 s68, s14, 11
	s_lshl_b32 s69, s15, 11
	s_lshl_b32 s70, s16, 11
	s_mov_b32 s82, s5
	v_lshl_add_u64 v[112:113], v[34:35], 0, s[0:1]
	v_cmp_ne_u32_e64 s[4:5], 1, v32
	v_add_u32_e32 v129, v36, v39
	v_add_u32_e32 v130, v40, v37
	v_mov_b32_e32 v131, 0x358637bd
	s_mov_b32 s71, 0xf800000
	v_mov_b32_e32 v132, 0x260
	v_readlane_b32 s95, v254, 60
	v_readlane_b32 s84, v254, 31
	v_readlane_b32 s85, v254, 32
	v_readlane_b32 s86, v254, 33
	v_readlane_b32 s87, v254, 34
	v_readlane_b32 s88, v254, 35
	v_readlane_b32 s89, v254, 36
	v_readlane_b32 s90, v254, 37
	v_readlane_b32 s91, v254, 38
	v_readlane_b32 s92, v254, 39
	v_readlane_b32 s93, v254, 40
	v_readlane_b32 s9, v254, 1
	s_branch .LBB0_746
.LBB0_745:
	v_add_u32_e32 v32, s29, v120
	s_waitcnt lgkmcnt(0)
	s_barrier
	ds_read_b128 v[36:39], v32 offset:63488
	ds_read_b128 v[32:35], v32 offset:63504
	s_lshl_b32 s1, s1, 11
	s_or_b32 s8, s1, s0
	s_add_i32 s7, s7, 32
	s_waitcnt lgkmcnt(1)
	v_mov_b32_e32 v40, v37
	v_mov_b32_e32 v41, v38
	v_mov_b32_e32 v116, v36
	v_mov_b32_e32 v117, v39
	v_pk_add_f32 v[40:41], v[40:41], v[116:117]
	s_waitcnt lgkmcnt(0)
	v_mov_b32_e32 v116, v34
	v_mov_b32_e32 v117, v32
	v_mov_b32_e32 v134, v35
	v_mov_b32_e32 v135, v33
	v_pk_add_f32 v[116:117], v[116:117], v[134:135]
	v_add_f32_e32 v40, v40, v41
	v_add_f32_e32 v40, v40, v117
	v_add_f32_e32 v40, v116, v40
	ds_bpermute_b32 v41, v121, v40
	s_mov_b32 s73, s72
	s_waitcnt lgkmcnt(0)
	v_add_f32_e32 v40, v40, v41
	ds_bpermute_b32 v41, v122, v40
	s_waitcnt lgkmcnt(0)
	v_add_f32_e32 v40, v40, v41
	ds_bpermute_b32 v41, v123, v40
	s_waitcnt lgkmcnt(0)
	v_add_f32_e32 v40, v40, v41
	ds_bpermute_b32 v41, v124, v40
	s_waitcnt lgkmcnt(0)
	v_add_f32_e32 v40, v40, v41
	ds_bpermute_b32 v41, v125, v40
	s_waitcnt lgkmcnt(0)
	v_add_f32_e32 v40, v40, v41
	ds_bpermute_b32 v41, v126, v40
	s_waitcnt lgkmcnt(0)
	v_add_f32_e32 v40, v40, v41
	v_fmamk_f32 v117, v40, 0xbb000000, v39
	v_fmac_f32_e32 v37, 0xbb000000, v40
	v_fmamk_f32 v116, v40, 0xbb000000, v38
	v_fmamk_f32 v36, v40, 0xbb000000, v36
	v_mul_f32_e32 v38, v37, v37
	v_mul_f32_e32 v39, v117, v117
	v_fmamk_f32 v33, v40, 0xbb000000, v33
	v_fmamk_f32 v32, v40, 0xbb000000, v32
	v_fmamk_f32 v35, v40, 0xbb000000, v35
	v_fmac_f32_e32 v34, 0xbb000000, v40
	v_fmac_f32_e32 v38, v36, v36
	v_fmac_f32_e32 v39, v116, v116
	v_add_f32_e32 v118, v38, v39
	v_pk_mul_f32 v[38:39], v[34:35], v[34:35]
	v_pk_mul_f32 v[40:41], v[32:33], v[32:33]
	v_mov_b32_e32 v134, v38
	v_mov_b32_e32 v135, v40
	v_mov_b32_e32 v40, v39
	v_pk_add_f32 v[38:39], v[134:135], v[40:41]
	s_nop 0
	v_add_f32_e32 v39, v39, v118
	v_add_f32_e32 v38, v38, v39
	ds_bpermute_b32 v39, v121, v38
	s_waitcnt lgkmcnt(0)
	v_add_f32_e32 v38, v38, v39
	ds_bpermute_b32 v39, v122, v38
	s_waitcnt lgkmcnt(0)
	v_add_f32_e32 v38, v38, v39
	ds_bpermute_b32 v39, v123, v38
	s_waitcnt lgkmcnt(0)
	v_add_f32_e32 v38, v38, v39
	ds_bpermute_b32 v39, v124, v38
	s_waitcnt lgkmcnt(0)
	v_add_f32_e32 v38, v38, v39
	ds_bpermute_b32 v39, v125, v38
	s_waitcnt lgkmcnt(0)
	v_add_f32_e32 v38, v38, v39
	ds_bpermute_b32 v39, v126, v38
	s_waitcnt lgkmcnt(0)
	v_add_f32_e32 v38, v38, v39
	v_fmamk_f32 v38, v38, 0x3b000000, v131
	v_cmp_gt_f32_e32 vcc, s71, v38
	v_mul_f32_e32 v39, 0x4f800000, v38
	s_nop 0
	v_cndmask_b32_e32 v38, v38, v39, vcc
	v_sqrt_f32_e32 v39, v38
	s_nop 0
	v_add_u32_e32 v40, -1, v39
	v_fma_f32 v41, -v40, v39, v38
	v_cmp_ge_f32_e64 s[0:1], 0, v41
	v_add_u32_e32 v41, 1, v39
	s_nop 0
	v_cndmask_b32_e64 v40, v39, v40, s[0:1]
	v_fma_f32 v39, -v41, v39, v38
	v_cmp_lt_f32_e64 s[0:1], 0, v39
	s_nop 1
	v_cndmask_b32_e64 v39, v40, v41, s[0:1]
	v_mul_f32_e32 v40, 0x37800000, v39
	v_cndmask_b32_e32 v39, v39, v40, vcc
	v_cmp_class_f32_e32 vcc, v38, v132
	s_nop 1
	v_cndmask_b32_e32 v38, v39, v38, vcc
	v_div_scale_f32 v39, s[0:1], v38, v38, 1.0
	v_rcp_f32_e32 v40, v39
	s_add_i32 s0, s8, s6
	s_ashr_i32 s1, s0, 31
	s_lshl_b64 s[0:1], s[0:1], 11
	v_fma_f32 v41, -v39, v40, 1.0
	v_fmac_f32_e32 v40, v41, v40
	v_div_scale_f32 v41, vcc, 1.0, v38, 1.0
	v_mul_f32_e32 v118, v41, v40
	v_fma_f32 v133, -v39, v118, v41
	v_fmac_f32_e32 v118, v133, v40
	v_fma_f32 v39, -v39, v118, v41
	v_div_fmas_f32 v39, v39, v40, v118
	v_div_fixup_f32 v118, v39, v38, 1.0
	s_nop 0
	s_nop 0
	s_nop 0
	s_nop 0
	v_pk_mul_f32 v[36:37], v[36:37], v[118:119] op_sel_hi:[1,0]
	v_pk_mul_f32 v[32:33], v[32:33], v[118:119] op_sel_hi:[1,0]
	v_pk_mul_f32 v[34:35], v[34:35], v[118:119] op_sel_hi:[1,0]
	v_pk_mul_f32 v[116:117], v[116:117], v[118:119] op_sel_hi:[1,0]
	s_waitcnt vmcnt(0)
	v_pk_fma_f32 v[40:41], v[230:231], v[34:35], v[238:239]
	s_nop 0
	v_pk_fma_f32 v[36:37], v[232:233], v[36:37], v[240:241]
	v_pk_fma_f32 v[34:35], v[228:229], v[32:33], v[236:237]
	v_mul_f32_e32 v32, 0xbfb8aa3b, v36
	v_mul_f32_e32 v33, 0xbfb8aa3b, v37
	v_exp_f32_e32 v32, v32
	v_exp_f32_e32 v33, v33
	v_pk_fma_f32 v[116:117], v[234:235], v[116:117], v[242:243]
	v_add_f32_e32 v32, 1.0, v32
	v_add_f32_e32 v33, 1.0, v33
	v_rcp_f32_e32 v32, v32
	v_rcp_f32_e32 v33, v33
	v_mul_f32_e32 v32, v36, v32
	v_mul_f32_e32 v33, v37, v33
	v_cvt_pk_bf16_f32 v32, v32, v33
	v_mul_f32_e32 v33, 0xbfb8aa3b, v116
	v_mul_f32_e32 v36, 0xbfb8aa3b, v117
	v_exp_f32_e32 v33, v33
	v_exp_f32_e32 v36, v36
	v_add_f32_e32 v33, 1.0, v33
	v_add_f32_e32 v36, 1.0, v36
	v_rcp_f32_e32 v33, v33
	v_rcp_f32_e32 v36, v36
	v_mul_f32_e32 v33, v116, v33
	v_mul_f32_e32 v36, v117, v36
	v_cvt_pk_bf16_f32 v33, v33, v36
	v_mul_f32_e32 v36, 0xbfb8aa3b, v34
	v_exp_f32_e32 v36, v36
	s_nop 0
	v_add_f32_e32 v36, 1.0, v36
	v_rcp_f32_e32 v36, v36
	s_nop 0
	v_mul_f32_e32 v34, v34, v36
	v_mul_f32_e32 v36, 0xbfb8aa3b, v35
	v_exp_f32_e32 v36, v36
	s_nop 0
	v_add_f32_e32 v36, 1.0, v36
	v_rcp_f32_e32 v36, v36
	s_nop 0
	v_mul_f32_e32 v35, v35, v36
	v_cvt_pk_bf16_f32 v34, v34, v35
	v_mul_f32_e32 v35, 0xbfb8aa3b, v40
	v_mul_f32_e32 v36, 0xbfb8aa3b, v41
	v_exp_f32_e32 v35, v35
	v_exp_f32_e32 v36, v36
	v_add_f32_e32 v35, 1.0, v35
	v_add_f32_e32 v36, 1.0, v36
	v_rcp_f32_e32 v35, v35
	v_rcp_f32_e32 v36, v36
	v_mul_f32_e32 v35, v40, v35
	v_mul_f32_e32 v36, v41, v36
	v_cvt_pk_bf16_f32 v35, v35, v36
	v_lshl_add_u64 v[36:37], v[114:115], 0, s[0:1]
	global_store_dwordx4 v[36:37], v[32:35], off offset:1024
	s_nop 1
	v_add_u32_e32 v32, s68, v120
	ds_read_b128 v[36:39], v32 offset:63488
	ds_read_b128 v[32:35], v32 offset:63504
	s_waitcnt lgkmcnt(1)
	v_mov_b32_e32 v40, v37
	v_mov_b32_e32 v41, v38
	v_mov_b32_e32 v116, v36
	v_mov_b32_e32 v117, v39
	v_pk_add_f32 v[40:41], v[40:41], v[116:117]
	s_waitcnt lgkmcnt(0)
	v_mov_b32_e32 v116, v34
	v_mov_b32_e32 v117, v32
	v_mov_b32_e32 v134, v35
	v_mov_b32_e32 v135, v33
	v_pk_add_f32 v[116:117], v[116:117], v[134:135]
	v_add_f32_e32 v40, v40, v41
	v_add_f32_e32 v40, v40, v117
	v_add_f32_e32 v40, v116, v40
	ds_bpermute_b32 v41, v121, v40
	s_waitcnt lgkmcnt(0)
	v_add_f32_e32 v40, v40, v41
	ds_bpermute_b32 v41, v122, v40
	s_waitcnt lgkmcnt(0)
	v_add_f32_e32 v40, v40, v41
	ds_bpermute_b32 v41, v123, v40
	s_waitcnt lgkmcnt(0)
	v_add_f32_e32 v40, v40, v41
	ds_bpermute_b32 v41, v124, v40
	s_waitcnt lgkmcnt(0)
	v_add_f32_e32 v40, v40, v41
	ds_bpermute_b32 v41, v125, v40
	s_waitcnt lgkmcnt(0)
	v_add_f32_e32 v40, v40, v41
	ds_bpermute_b32 v41, v126, v40
	s_waitcnt lgkmcnt(0)
	v_add_f32_e32 v40, v40, v41
	v_fmamk_f32 v117, v40, 0xbb000000, v39
	v_fmac_f32_e32 v37, 0xbb000000, v40
	v_fmamk_f32 v116, v40, 0xbb000000, v38
	v_fmamk_f32 v36, v40, 0xbb000000, v36
	v_mul_f32_e32 v38, v37, v37
	v_mul_f32_e32 v39, v117, v117
	v_fmamk_f32 v33, v40, 0xbb000000, v33
	v_fmamk_f32 v32, v40, 0xbb000000, v32
	v_fmamk_f32 v35, v40, 0xbb000000, v35
	v_fmac_f32_e32 v34, 0xbb000000, v40
	v_fmac_f32_e32 v38, v36, v36
	v_fmac_f32_e32 v39, v116, v116
	v_add_f32_e32 v118, v38, v39
	v_pk_mul_f32 v[38:39], v[34:35], v[34:35]
	v_pk_mul_f32 v[40:41], v[32:33], v[32:33]
	v_mov_b32_e32 v134, v38
	v_mov_b32_e32 v135, v40
	v_mov_b32_e32 v40, v39
	v_pk_add_f32 v[38:39], v[134:135], v[40:41]
	s_nop 0
	v_add_f32_e32 v39, v39, v118
	v_add_f32_e32 v38, v38, v39
	ds_bpermute_b32 v39, v121, v38
	s_waitcnt lgkmcnt(0)
	v_add_f32_e32 v38, v38, v39
	ds_bpermute_b32 v39, v122, v38
	s_waitcnt lgkmcnt(0)
	v_add_f32_e32 v38, v38, v39
	ds_bpermute_b32 v39, v123, v38
	s_waitcnt lgkmcnt(0)
	v_add_f32_e32 v38, v38, v39
	ds_bpermute_b32 v39, v124, v38
	s_waitcnt lgkmcnt(0)
	v_add_f32_e32 v38, v38, v39
	ds_bpermute_b32 v39, v125, v38
	s_waitcnt lgkmcnt(0)
	v_add_f32_e32 v38, v38, v39
	ds_bpermute_b32 v39, v126, v38
	s_waitcnt lgkmcnt(0)
	v_add_f32_e32 v38, v38, v39
	v_fmamk_f32 v38, v38, 0x3b000000, v131
	v_cmp_gt_f32_e32 vcc, s71, v38
	v_mul_f32_e32 v39, 0x4f800000, v38
	s_nop 0
	v_cndmask_b32_e32 v38, v38, v39, vcc
	v_sqrt_f32_e32 v39, v38
	s_nop 0
	v_add_u32_e32 v40, -1, v39
	v_fma_f32 v41, -v40, v39, v38
	v_cmp_ge_f32_e64 s[0:1], 0, v41
	v_add_u32_e32 v41, 1, v39
	s_nop 0
	v_cndmask_b32_e64 v40, v39, v40, s[0:1]
	v_fma_f32 v39, -v41, v39, v38
	v_cmp_lt_f32_e64 s[0:1], 0, v39
	s_nop 1
	v_cndmask_b32_e64 v39, v40, v41, s[0:1]
	v_mul_f32_e32 v40, 0x37800000, v39
	v_cndmask_b32_e32 v39, v39, v40, vcc
	v_cmp_class_f32_e32 vcc, v38, v132
	s_nop 1
	v_cndmask_b32_e32 v38, v39, v38, vcc
	v_div_scale_f32 v39, s[0:1], v38, v38, 1.0
	v_rcp_f32_e32 v40, v39
	s_add_i32 s0, s8, s14
	s_ashr_i32 s1, s0, 31
	s_lshl_b64 s[0:1], s[0:1], 11
	v_fma_f32 v41, -v39, v40, 1.0
	v_fmac_f32_e32 v40, v41, v40
	v_div_scale_f32 v41, vcc, 1.0, v38, 1.0
	v_mul_f32_e32 v118, v41, v40
	v_fma_f32 v133, -v39, v118, v41
	v_fmac_f32_e32 v118, v133, v40
	v_fma_f32 v39, -v39, v118, v41
	v_div_fmas_f32 v39, v39, v40, v118
	v_div_fixup_f32 v118, v39, v38, 1.0
	s_nop 0
	s_nop 0
	s_nop 0
	s_nop 0
	v_pk_mul_f32 v[36:37], v[36:37], v[118:119] op_sel_hi:[1,0]
	v_pk_mul_f32 v[32:33], v[32:33], v[118:119] op_sel_hi:[1,0]
	v_pk_mul_f32 v[34:35], v[34:35], v[118:119] op_sel_hi:[1,0]
	v_pk_mul_f32 v[116:117], v[116:117], v[118:119] op_sel_hi:[1,0]
	s_nop 0
	v_pk_fma_f32 v[40:41], v[230:231], v[34:35], v[238:239]
	s_nop 0
	v_pk_fma_f32 v[36:37], v[232:233], v[36:37], v[240:241]
	v_pk_fma_f32 v[34:35], v[228:229], v[32:33], v[236:237]
	v_mul_f32_e32 v32, 0xbfb8aa3b, v36
	v_mul_f32_e32 v33, 0xbfb8aa3b, v37
	v_exp_f32_e32 v32, v32
	v_exp_f32_e32 v33, v33
	v_pk_fma_f32 v[116:117], v[234:235], v[116:117], v[242:243]
	v_add_f32_e32 v32, 1.0, v32
	v_add_f32_e32 v33, 1.0, v33
	v_rcp_f32_e32 v32, v32
	v_rcp_f32_e32 v33, v33
	v_mul_f32_e32 v32, v36, v32
	v_mul_f32_e32 v33, v37, v33
	v_cvt_pk_bf16_f32 v32, v32, v33
	v_mul_f32_e32 v33, 0xbfb8aa3b, v116
	v_mul_f32_e32 v36, 0xbfb8aa3b, v117
	v_exp_f32_e32 v33, v33
	v_exp_f32_e32 v36, v36
	v_add_f32_e32 v33, 1.0, v33
	v_add_f32_e32 v36, 1.0, v36
	v_rcp_f32_e32 v33, v33
	v_rcp_f32_e32 v36, v36
	v_mul_f32_e32 v33, v116, v33
	v_mul_f32_e32 v36, v117, v36
	v_cvt_pk_bf16_f32 v33, v33, v36
	v_mul_f32_e32 v36, 0xbfb8aa3b, v34
	v_exp_f32_e32 v36, v36
	s_nop 0
	v_add_f32_e32 v36, 1.0, v36
	v_rcp_f32_e32 v36, v36
	s_nop 0
	v_mul_f32_e32 v34, v34, v36
	v_mul_f32_e32 v36, 0xbfb8aa3b, v35
	v_exp_f32_e32 v36, v36
	s_nop 0
	v_add_f32_e32 v36, 1.0, v36
	v_rcp_f32_e32 v36, v36
	s_nop 0
	v_mul_f32_e32 v35, v35, v36
	v_cvt_pk_bf16_f32 v34, v34, v35
	v_mul_f32_e32 v35, 0xbfb8aa3b, v40
	v_mul_f32_e32 v36, 0xbfb8aa3b, v41
	v_exp_f32_e32 v35, v35
	v_exp_f32_e32 v36, v36
	v_add_f32_e32 v35, 1.0, v35
	v_add_f32_e32 v36, 1.0, v36
	v_rcp_f32_e32 v35, v35
	v_rcp_f32_e32 v36, v36
	v_mul_f32_e32 v35, v40, v35
	v_mul_f32_e32 v36, v41, v36
	v_cvt_pk_bf16_f32 v35, v35, v36
	v_lshl_add_u64 v[36:37], v[114:115], 0, s[0:1]
	global_store_dwordx4 v[36:37], v[32:35], off offset:1024
	s_nop 1
	v_add_u32_e32 v32, s69, v120
	ds_read_b128 v[36:39], v32 offset:63488
	ds_read_b128 v[32:35], v32 offset:63504
	s_waitcnt lgkmcnt(1)
	v_mov_b32_e32 v40, v37
	v_mov_b32_e32 v41, v38
	v_mov_b32_e32 v116, v36
	v_mov_b32_e32 v117, v39
	v_pk_add_f32 v[40:41], v[40:41], v[116:117]
	s_waitcnt lgkmcnt(0)
	v_mov_b32_e32 v116, v34
	v_mov_b32_e32 v117, v32
	v_mov_b32_e32 v134, v35
	v_mov_b32_e32 v135, v33
	v_pk_add_f32 v[116:117], v[116:117], v[134:135]
	v_add_f32_e32 v40, v40, v41
	v_add_f32_e32 v40, v40, v117
	v_add_f32_e32 v40, v116, v40
	ds_bpermute_b32 v41, v121, v40
	s_waitcnt lgkmcnt(0)
	v_add_f32_e32 v40, v40, v41
	ds_bpermute_b32 v41, v122, v40
	s_waitcnt lgkmcnt(0)
	v_add_f32_e32 v40, v40, v41
	ds_bpermute_b32 v41, v123, v40
	s_waitcnt lgkmcnt(0)
	v_add_f32_e32 v40, v40, v41
	ds_bpermute_b32 v41, v124, v40
	s_waitcnt lgkmcnt(0)
	v_add_f32_e32 v40, v40, v41
	ds_bpermute_b32 v41, v125, v40
	s_waitcnt lgkmcnt(0)
	v_add_f32_e32 v40, v40, v41
	ds_bpermute_b32 v41, v126, v40
	s_waitcnt lgkmcnt(0)
	v_add_f32_e32 v40, v40, v41
	v_fmamk_f32 v117, v40, 0xbb000000, v39
	v_fmac_f32_e32 v37, 0xbb000000, v40
	v_fmamk_f32 v116, v40, 0xbb000000, v38
	v_fmamk_f32 v36, v40, 0xbb000000, v36
	v_mul_f32_e32 v38, v37, v37
	v_mul_f32_e32 v39, v117, v117
	v_fmamk_f32 v33, v40, 0xbb000000, v33
	v_fmamk_f32 v32, v40, 0xbb000000, v32
	v_fmamk_f32 v35, v40, 0xbb000000, v35
	v_fmac_f32_e32 v34, 0xbb000000, v40
	v_fmac_f32_e32 v38, v36, v36
	v_fmac_f32_e32 v39, v116, v116
	v_add_f32_e32 v118, v38, v39
	v_pk_mul_f32 v[38:39], v[34:35], v[34:35]
	v_pk_mul_f32 v[40:41], v[32:33], v[32:33]
	v_mov_b32_e32 v134, v38
	v_mov_b32_e32 v135, v40
	v_mov_b32_e32 v40, v39
	v_pk_add_f32 v[38:39], v[134:135], v[40:41]
	s_nop 0
	v_add_f32_e32 v39, v39, v118
	v_add_f32_e32 v38, v38, v39
	ds_bpermute_b32 v39, v121, v38
	s_waitcnt lgkmcnt(0)
	v_add_f32_e32 v38, v38, v39
	ds_bpermute_b32 v39, v122, v38
	s_waitcnt lgkmcnt(0)
	v_add_f32_e32 v38, v38, v39
	ds_bpermute_b32 v39, v123, v38
	s_waitcnt lgkmcnt(0)
	v_add_f32_e32 v38, v38, v39
	ds_bpermute_b32 v39, v124, v38
	s_waitcnt lgkmcnt(0)
	v_add_f32_e32 v38, v38, v39
	ds_bpermute_b32 v39, v125, v38
	s_waitcnt lgkmcnt(0)
	v_add_f32_e32 v38, v38, v39
	ds_bpermute_b32 v39, v126, v38
	s_waitcnt lgkmcnt(0)
	v_add_f32_e32 v38, v38, v39
	v_fmamk_f32 v38, v38, 0x3b000000, v131
	v_cmp_gt_f32_e32 vcc, s71, v38
	v_mul_f32_e32 v39, 0x4f800000, v38
	s_nop 0
	v_cndmask_b32_e32 v38, v38, v39, vcc
	v_sqrt_f32_e32 v39, v38
	s_nop 0
	v_add_u32_e32 v40, -1, v39
	v_fma_f32 v41, -v40, v39, v38
	v_cmp_ge_f32_e64 s[0:1], 0, v41
	v_add_u32_e32 v41, 1, v39
	s_nop 0
	v_cndmask_b32_e64 v40, v39, v40, s[0:1]
	v_fma_f32 v39, -v41, v39, v38
	v_cmp_lt_f32_e64 s[0:1], 0, v39
	s_nop 1
	v_cndmask_b32_e64 v39, v40, v41, s[0:1]
	v_mul_f32_e32 v40, 0x37800000, v39
	v_cndmask_b32_e32 v39, v39, v40, vcc
	v_cmp_class_f32_e32 vcc, v38, v132
	s_nop 1
	v_cndmask_b32_e32 v38, v39, v38, vcc
	v_div_scale_f32 v39, s[0:1], v38, v38, 1.0
	v_rcp_f32_e32 v40, v39
	s_add_i32 s0, s8, s15
	s_ashr_i32 s1, s0, 31
	s_lshl_b64 s[0:1], s[0:1], 11
	v_fma_f32 v41, -v39, v40, 1.0
	v_fmac_f32_e32 v40, v41, v40
	v_div_scale_f32 v41, vcc, 1.0, v38, 1.0
	v_mul_f32_e32 v118, v41, v40
	v_fma_f32 v133, -v39, v118, v41
	v_fmac_f32_e32 v118, v133, v40
	v_fma_f32 v39, -v39, v118, v41
	v_div_fmas_f32 v39, v39, v40, v118
	v_div_fixup_f32 v118, v39, v38, 1.0
	s_nop 0
	s_nop 0
	s_nop 0
	s_nop 0
	v_pk_mul_f32 v[36:37], v[36:37], v[118:119] op_sel_hi:[1,0]
	v_pk_mul_f32 v[32:33], v[32:33], v[118:119] op_sel_hi:[1,0]
	v_pk_mul_f32 v[34:35], v[34:35], v[118:119] op_sel_hi:[1,0]
	v_pk_mul_f32 v[116:117], v[116:117], v[118:119] op_sel_hi:[1,0]
	s_nop 0
	v_pk_fma_f32 v[40:41], v[230:231], v[34:35], v[238:239]
	s_nop 0
	v_pk_fma_f32 v[36:37], v[232:233], v[36:37], v[240:241]
	v_pk_fma_f32 v[34:35], v[228:229], v[32:33], v[236:237]
	v_mul_f32_e32 v32, 0xbfb8aa3b, v36
	v_mul_f32_e32 v33, 0xbfb8aa3b, v37
	v_exp_f32_e32 v32, v32
	v_exp_f32_e32 v33, v33
	v_pk_fma_f32 v[116:117], v[234:235], v[116:117], v[242:243]
	v_add_f32_e32 v32, 1.0, v32
	v_add_f32_e32 v33, 1.0, v33
	v_rcp_f32_e32 v32, v32
	v_rcp_f32_e32 v33, v33
	v_mul_f32_e32 v32, v36, v32
	v_mul_f32_e32 v33, v37, v33
	v_cvt_pk_bf16_f32 v32, v32, v33
	v_mul_f32_e32 v33, 0xbfb8aa3b, v116
	v_mul_f32_e32 v36, 0xbfb8aa3b, v117
	v_exp_f32_e32 v33, v33
	v_exp_f32_e32 v36, v36
	v_add_f32_e32 v33, 1.0, v33
	v_add_f32_e32 v36, 1.0, v36
	v_rcp_f32_e32 v33, v33
	v_rcp_f32_e32 v36, v36
	v_mul_f32_e32 v33, v116, v33
	v_mul_f32_e32 v36, v117, v36
	v_cvt_pk_bf16_f32 v33, v33, v36
	v_mul_f32_e32 v36, 0xbfb8aa3b, v34
	v_exp_f32_e32 v36, v36
	s_nop 0
	v_add_f32_e32 v36, 1.0, v36
	v_rcp_f32_e32 v36, v36
	s_nop 0
	v_mul_f32_e32 v34, v34, v36
	v_mul_f32_e32 v36, 0xbfb8aa3b, v35
	v_exp_f32_e32 v36, v36
	s_nop 0
	v_add_f32_e32 v36, 1.0, v36
	v_rcp_f32_e32 v36, v36
	s_nop 0
	v_mul_f32_e32 v35, v35, v36
	v_cvt_pk_bf16_f32 v34, v34, v35
	v_mul_f32_e32 v35, 0xbfb8aa3b, v40
	v_mul_f32_e32 v36, 0xbfb8aa3b, v41
	v_exp_f32_e32 v35, v35
	v_exp_f32_e32 v36, v36
	v_add_f32_e32 v35, 1.0, v35
	v_add_f32_e32 v36, 1.0, v36
	v_rcp_f32_e32 v35, v35
	v_rcp_f32_e32 v36, v36
	v_mul_f32_e32 v35, v40, v35
	v_mul_f32_e32 v36, v41, v36
	v_cvt_pk_bf16_f32 v35, v35, v36
	v_lshl_add_u64 v[36:37], v[114:115], 0, s[0:1]
	global_store_dwordx4 v[36:37], v[32:35], off offset:1024
	s_nop 1
	v_add_u32_e32 v32, s70, v120
	ds_read_b128 v[36:39], v32 offset:63488
	ds_read_b128 v[32:35], v32 offset:63504
	s_waitcnt lgkmcnt(1)
	v_mov_b32_e32 v40, v37
	v_mov_b32_e32 v41, v38
	v_mov_b32_e32 v116, v36
	v_mov_b32_e32 v117, v39
	v_pk_add_f32 v[40:41], v[40:41], v[116:117]
	s_waitcnt lgkmcnt(0)
	v_mov_b32_e32 v116, v34
	v_mov_b32_e32 v117, v32
	v_mov_b32_e32 v134, v35
	v_mov_b32_e32 v135, v33
	v_pk_add_f32 v[116:117], v[116:117], v[134:135]
	v_add_f32_e32 v40, v40, v41
	v_add_f32_e32 v40, v40, v117
	v_add_f32_e32 v40, v116, v40
	ds_bpermute_b32 v41, v121, v40
	s_waitcnt lgkmcnt(0)
	v_add_f32_e32 v40, v40, v41
	ds_bpermute_b32 v41, v122, v40
	s_waitcnt lgkmcnt(0)
	v_add_f32_e32 v40, v40, v41
	ds_bpermute_b32 v41, v123, v40
	s_waitcnt lgkmcnt(0)
	v_add_f32_e32 v40, v40, v41
	ds_bpermute_b32 v41, v124, v40
	s_waitcnt lgkmcnt(0)
	v_add_f32_e32 v40, v40, v41
	ds_bpermute_b32 v41, v125, v40
	s_waitcnt lgkmcnt(0)
	v_add_f32_e32 v40, v40, v41
	ds_bpermute_b32 v41, v126, v40
	s_waitcnt lgkmcnt(0)
	v_add_f32_e32 v40, v40, v41
	v_fmamk_f32 v117, v40, 0xbb000000, v39
	v_fmac_f32_e32 v37, 0xbb000000, v40
	v_fmamk_f32 v116, v40, 0xbb000000, v38
	v_fmamk_f32 v36, v40, 0xbb000000, v36
	v_mul_f32_e32 v38, v37, v37
	v_mul_f32_e32 v39, v117, v117
	v_fmamk_f32 v33, v40, 0xbb000000, v33
	v_fmamk_f32 v32, v40, 0xbb000000, v32
	v_fmamk_f32 v35, v40, 0xbb000000, v35
	v_fmac_f32_e32 v34, 0xbb000000, v40
	v_fmac_f32_e32 v38, v36, v36
	v_fmac_f32_e32 v39, v116, v116
	v_add_f32_e32 v118, v38, v39
	v_pk_mul_f32 v[38:39], v[34:35], v[34:35]
	v_pk_mul_f32 v[40:41], v[32:33], v[32:33]
	v_mov_b32_e32 v134, v38
	v_mov_b32_e32 v135, v40
	v_mov_b32_e32 v40, v39
	v_pk_add_f32 v[38:39], v[134:135], v[40:41]
	s_nop 0
	v_add_f32_e32 v39, v39, v118
	v_add_f32_e32 v38, v38, v39
	ds_bpermute_b32 v39, v121, v38
	s_waitcnt lgkmcnt(0)
	v_add_f32_e32 v38, v38, v39
	ds_bpermute_b32 v39, v122, v38
	s_waitcnt lgkmcnt(0)
	v_add_f32_e32 v38, v38, v39
	ds_bpermute_b32 v39, v123, v38
	s_waitcnt lgkmcnt(0)
	v_add_f32_e32 v38, v38, v39
	ds_bpermute_b32 v39, v124, v38
	s_waitcnt lgkmcnt(0)
	v_add_f32_e32 v38, v38, v39
	ds_bpermute_b32 v39, v125, v38
	s_waitcnt lgkmcnt(0)
	v_add_f32_e32 v38, v38, v39
	ds_bpermute_b32 v39, v126, v38
	s_waitcnt lgkmcnt(0)
	v_add_f32_e32 v38, v38, v39
	v_fmamk_f32 v38, v38, 0x3b000000, v131
	v_cmp_gt_f32_e32 vcc, s71, v38
	v_mul_f32_e32 v39, 0x4f800000, v38
	s_nop 0
	v_cndmask_b32_e32 v38, v38, v39, vcc
	v_sqrt_f32_e32 v39, v38
	s_nop 0
	v_add_u32_e32 v40, -1, v39
	v_fma_f32 v41, -v40, v39, v38
	v_cmp_ge_f32_e64 s[0:1], 0, v41
	v_add_u32_e32 v41, 1, v39
	s_nop 0
	v_cndmask_b32_e64 v40, v39, v40, s[0:1]
	v_fma_f32 v39, -v41, v39, v38
	v_cmp_lt_f32_e64 s[0:1], 0, v39
	s_nop 1
	v_cndmask_b32_e64 v39, v40, v41, s[0:1]
	v_mul_f32_e32 v40, 0x37800000, v39
	v_cndmask_b32_e32 v39, v39, v40, vcc
	v_cmp_class_f32_e32 vcc, v38, v132
	s_nop 1
	v_cndmask_b32_e32 v38, v39, v38, vcc
	v_div_scale_f32 v39, s[0:1], v38, v38, 1.0
	v_rcp_f32_e32 v40, v39
	s_add_i32 s0, s8, s16
	s_ashr_i32 s1, s0, 31
	s_lshl_b64 s[0:1], s[0:1], 11
	v_fma_f32 v41, -v39, v40, 1.0
	v_fmac_f32_e32 v40, v41, v40
	v_div_scale_f32 v41, vcc, 1.0, v38, 1.0
	v_mul_f32_e32 v118, v41, v40
	v_fma_f32 v133, -v39, v118, v41
	v_fmac_f32_e32 v118, v133, v40
	v_fma_f32 v39, -v39, v118, v41
	v_div_fmas_f32 v39, v39, v40, v118
	v_div_fixup_f32 v118, v39, v38, 1.0
	s_nop 0
	s_nop 0
	s_nop 0
	s_nop 0
	v_pk_mul_f32 v[36:37], v[36:37], v[118:119] op_sel_hi:[1,0]
	v_pk_mul_f32 v[32:33], v[32:33], v[118:119] op_sel_hi:[1,0]
	v_pk_mul_f32 v[34:35], v[34:35], v[118:119] op_sel_hi:[1,0]
	v_pk_mul_f32 v[116:117], v[116:117], v[118:119] op_sel_hi:[1,0]
	s_andn2_b64 vcc, exec, s[90:91]
	s_nop 0
	v_pk_fma_f32 v[40:41], v[230:231], v[34:35], v[238:239]
	s_nop 0
	v_pk_fma_f32 v[36:37], v[232:233], v[36:37], v[240:241]
	v_pk_fma_f32 v[34:35], v[228:229], v[32:33], v[236:237]
	v_mul_f32_e32 v32, 0xbfb8aa3b, v36
	v_mul_f32_e32 v33, 0xbfb8aa3b, v37
	v_exp_f32_e32 v32, v32
	v_exp_f32_e32 v33, v33
	v_pk_fma_f32 v[116:117], v[234:235], v[116:117], v[242:243]
	v_add_f32_e32 v32, 1.0, v32
	v_add_f32_e32 v33, 1.0, v33
	v_rcp_f32_e32 v32, v32
	v_rcp_f32_e32 v33, v33
	v_mul_f32_e32 v32, v36, v32
	v_mul_f32_e32 v33, v37, v33
	v_cvt_pk_bf16_f32 v32, v32, v33
	v_mul_f32_e32 v33, 0xbfb8aa3b, v116
	v_mul_f32_e32 v36, 0xbfb8aa3b, v117
	v_exp_f32_e32 v33, v33
	v_exp_f32_e32 v36, v36
	v_add_f32_e32 v33, 1.0, v33
	v_add_f32_e32 v36, 1.0, v36
	v_rcp_f32_e32 v33, v33
	v_rcp_f32_e32 v36, v36
	v_mul_f32_e32 v33, v116, v33
	v_mul_f32_e32 v36, v117, v36
	v_cvt_pk_bf16_f32 v33, v33, v36
	v_mul_f32_e32 v36, 0xbfb8aa3b, v34
	v_exp_f32_e32 v36, v36
	s_nop 0
	v_add_f32_e32 v36, 1.0, v36
	v_rcp_f32_e32 v36, v36
	s_nop 0
	v_mul_f32_e32 v34, v34, v36
	v_mul_f32_e32 v36, 0xbfb8aa3b, v35
	v_exp_f32_e32 v36, v36
	s_nop 0
	v_add_f32_e32 v36, 1.0, v36
	v_rcp_f32_e32 v36, v36
	s_nop 0
	v_mul_f32_e32 v35, v35, v36
	v_cvt_pk_bf16_f32 v34, v34, v35
	v_mul_f32_e32 v35, 0xbfb8aa3b, v40
	v_mul_f32_e32 v36, 0xbfb8aa3b, v41
	v_exp_f32_e32 v35, v35
	v_exp_f32_e32 v36, v36
	v_add_f32_e32 v35, 1.0, v35
	v_add_f32_e32 v36, 1.0, v36
	v_rcp_f32_e32 v35, v35
	v_rcp_f32_e32 v36, v36
	v_mul_f32_e32 v35, v40, v35
	v_mul_f32_e32 v36, v41, v36
	v_cvt_pk_bf16_f32 v35, v35, v36
	v_lshl_add_u64 v[36:37], v[114:115], 0, s[0:1]
	global_store_dwordx4 v[36:37], v[32:35], off offset:1024
	s_barrier
	s_cbranch_vccz .LBB0_781
